# GEMM: first K-iteration peeled with C=0 (no accumulator zeroing per unit); barrier non-leaders poll top generation; SB Q-tile loads batched
# speedup vs baseline: 1.0054x; 1.0054x over previous
.LBB0_167:
	s_bfe_u32 s47, s45, 0x10002
	s_ashr_i32 s6, s45, 3
	s_lshl_b32 s7, s47, 27
	s_add_u32 s92, s78, s7
	s_addc_u32 s93, s79, 0
	s_lshl_b32 s7, s45, 8
	s_and_b32 s7, s7, 0x300
	s_lshl_b32 s48, s6, 7
	s_lshl_b32 s36, s7, 1
	s_add_u32 s8, s92, s36
	v_add_u32_e32 v0, s48, v148
	s_addc_u32 s9, s93, 0
	v_mov_b32_e32 v137, v81
	v_ashrrev_i32_e32 v1, 31, v0
	v_lshl_add_u64 v[138:139], s[8:9], 0, v[136:137]
	v_lshlrev_b64 v[0:1], 13, v[0:1]
	v_lshl_add_u64 v[0:1], v[138:139], 0, v[0:1]
	global_load_dwordx4 v[0:3], v[0:1], off
	v_add_u32_e32 v192, s48, v150
	v_ashrrev_i32_e32 v193, 31, v192
	v_lshlrev_b64 v[192:193], 13, v[192:193]
	v_lshl_add_u64 v[192:193], v[138:139], 0, v[192:193]
	global_load_dwordx4 v[192:195], v[192:193], off
	v_add_u32_e32 v196, s48, v152
	v_ashrrev_i32_e32 v197, 31, v196
	v_lshlrev_b64 v[196:197], 13, v[196:197]
	v_lshl_add_u64 v[196:197], v[138:139], 0, v[196:197]
	global_load_dwordx4 v[196:199], v[196:197], off
	v_add_u32_e32 v200, s48, v153
	v_ashrrev_i32_e32 v201, 31, v200
	v_lshlrev_b64 v[200:201], 13, v[200:201]
	v_lshl_add_u64 v[200:201], v[138:139], 0, v[200:201]
	global_load_dwordx4 v[200:203], v[200:201], off
	v_add_u32_e32 v204, s48, v154
	v_ashrrev_i32_e32 v205, 31, v204
	v_lshlrev_b64 v[204:205], 13, v[204:205]
	v_lshl_add_u64 v[204:205], v[138:139], 0, v[204:205]
	global_load_dwordx4 v[204:207], v[204:205], off
	v_add_u32_e32 v216, s48, v155
	v_ashrrev_i32_e32 v217, 31, v216
	v_lshlrev_b64 v[216:217], 13, v[216:217]
	v_lshl_add_u64 v[216:217], v[138:139], 0, v[216:217]
	global_load_dwordx4 v[216:219], v[216:217], off
	v_add_u32_e32 v220, s48, v156
	v_ashrrev_i32_e32 v221, 31, v220
	v_lshlrev_b64 v[220:221], 13, v[220:221]
	v_lshl_add_u64 v[220:221], v[138:139], 0, v[220:221]
	global_load_dwordx4 v[220:223], v[220:221], off
	v_add_u32_e32 v224, s48, v157
	v_ashrrev_i32_e32 v225, 31, v224
	v_lshlrev_b64 v[224:225], 13, v[224:225]
	v_lshl_add_u64 v[224:225], v[138:139], 0, v[224:225]
	global_load_dwordx4 v[224:227], v[224:225], off
	s_lshl_b32 s7, s6, 2
	s_or_b32 s49, s7, 3
	s_lshl_b32 s7, s49, 5
	s_cmp_lt_i32 s6, 0
	v_add_u32_e32 v4, v99, v149
	s_waitcnt vmcnt(7)
	ds_write_b128 v4, v[0:3]
	v_add_u32_e32 v4, v99, v151
	s_waitcnt vmcnt(6)
	ds_write_b128 v4, v[192:195]
	s_waitcnt vmcnt(5)
	ds_write_b128 v171, v[196:199]
	s_waitcnt vmcnt(4)
	ds_write_b128 v172, v[200:203]
	s_waitcnt vmcnt(3)
	ds_write_b128 v173, v[204:207]
	s_waitcnt vmcnt(2)
	ds_write_b128 v174, v[216:219]
	s_waitcnt vmcnt(1)
	ds_write_b128 v175, v[220:223]
	s_waitcnt vmcnt(0)
	ds_write_b128 v176, v[224:227]
	v_or_b32_e32 v0, s7, v98
	v_add_u32_e32 v2, s7, v148
	v_ashrrev_i32_e32 v1, 31, v0
	v_ashrrev_i32_e32 v3, 31, v2
	v_lshlrev_b64 v[0:1], 13, v[0:1]
	v_lshlrev_b64 v[2:3], 13, v[2:3]
	v_lshl_add_u64 v[0:1], s[92:93], 0, v[0:1]
	v_lshl_add_u64 v[2:3], s[92:93], 0, v[2:3]
	v_lshl_add_u64 v[0:1], v[0:1], 0, s[36:37]
	v_lshl_add_u64 v[2:3], v[2:3], 0, s[36:37]
	v_lshl_add_u64 v[0:1], v[0:1], 0, s[70:71]
	v_lshl_add_u64 v[2:3], v[2:3], 0, v[136:137]
	global_load_dwordx4 v[82:85], v[2:3], off offset:2048
	v_lshl_add_u64 v[2:3], v[100:101], 1, v[0:1]
	v_lshl_add_u64 v[0:1], v[102:103], 1, v[0:1]
	global_load_dwordx4 v[86:89], v[2:3], off
	global_load_dwordx4 v[94:97], v[0:1], off
	v_add_u32_e32 v2, s7, v150
	v_ashrrev_i32_e32 v3, 31, v2
	v_lshlrev_b64 v[2:3], 13, v[2:3]
	v_lshl_add_u64 v[2:3], s[92:93], 0, v[2:3]
	v_lshl_add_u64 v[2:3], v[2:3], 0, s[36:37]
	v_lshl_add_u64 v[2:3], v[2:3], 0, v[136:137]
	global_load_dwordx4 v[90:93], v[2:3], off offset:2048
	v_add_u32_e32 v0, v159, v149
	s_waitcnt vmcnt(3)
	ds_write_b128 v0, v[82:85]
	v_add_u32_e32 v0, v160, v161
	s_waitcnt vmcnt(2)
	ds_write_b16 v0, v86 offset:33792
	ds_write_b16_d16_hi v0, v86 offset:33864
	ds_write_b16 v0, v87 offset:33936
	ds_write_b16_d16_hi v0, v87 offset:34008
	ds_write_b16 v0, v88 offset:34080
	ds_write_b16_d16_hi v0, v88 offset:34152
	ds_write_b16 v0, v89 offset:34224
	ds_write_b16_d16_hi v0, v89 offset:34296
	v_add_u32_e32 v0, v159, v151
	s_waitcnt vmcnt(0)
	ds_write_b128 v0, v[90:93]
	v_add_u32_e32 v0, v160, v166
	ds_write_b16 v0, v94 offset:33792
	ds_write_b16_d16_hi v0, v94 offset:33864
	ds_write_b16 v0, v95 offset:33936
	ds_write_b16_d16_hi v0, v95 offset:34008
	ds_write_b16 v0, v96 offset:34080
	ds_write_b16_d16_hi v0, v96 offset:34152
	ds_write_b16 v0, v97 offset:34224
	ds_write_b16_d16_hi v0, v97 offset:34296
	s_waitcnt lgkmcnt(0)
	s_barrier
	s_cbranch_scc1 .LBB0_181
	s_or_b32 s6, s48, s33
	v_mov_b32_e32 v141, 0
	v_or_b32_e32 v137, s6, v98
	s_or_b32 s50, s6, 31
	s_mov_b64 s[94:95], 0
	v_mov_b32_e32 v48, v141
	v_mov_b32_e32 v49, v141
	v_mov_b32_e32 v50, v141
	v_mov_b32_e32 v51, v141
	v_mov_b32_e32 v52, v141
	v_mov_b32_e32 v53, v141
	v_mov_b32_e32 v54, v141
	v_mov_b32_e32 v55, v141
	v_mov_b32_e32 v56, v141
	v_mov_b32_e32 v57, v141
	v_mov_b32_e32 v58, v141
	v_mov_b32_e32 v59, v141
	v_mov_b32_e32 v60, v141
	v_mov_b32_e32 v61, v141
	v_mov_b32_e32 v62, v141
	v_mov_b32_e32 v63, v141
	v_mov_b32_e32 v32, v141
	v_mov_b32_e32 v33, v141
	v_mov_b32_e32 v34, v141
	v_mov_b32_e32 v35, v141
	v_mov_b32_e32 v36, v141
	v_mov_b32_e32 v37, v141
	v_mov_b32_e32 v38, v141
	v_mov_b32_e32 v39, v141
	v_mov_b32_e32 v40, v141
	v_mov_b32_e32 v41, v141
	v_mov_b32_e32 v42, v141
	v_mov_b32_e32 v43, v141
	v_mov_b32_e32 v44, v141
	v_mov_b32_e32 v45, v141
	v_mov_b32_e32 v46, v141
	v_mov_b32_e32 v47, v141
	v_mov_b32_e32 v16, v141
	v_mov_b32_e32 v17, v141
	v_mov_b32_e32 v18, v141
	v_mov_b32_e32 v19, v141
	v_mov_b32_e32 v20, v141
	v_mov_b32_e32 v21, v141
	v_mov_b32_e32 v22, v141
	v_mov_b32_e32 v23, v141
	v_mov_b32_e32 v24, v141
	v_mov_b32_e32 v25, v141
	v_mov_b32_e32 v26, v141
	v_mov_b32_e32 v27, v141
	v_mov_b32_e32 v28, v141
	v_mov_b32_e32 v29, v141
	v_mov_b32_e32 v30, v141
	v_mov_b32_e32 v31, v141
	v_mov_b32_e32 v0, v141
	v_mov_b32_e32 v1, v141
	v_mov_b32_e32 v2, v141
	v_mov_b32_e32 v3, v141
	v_mov_b32_e32 v4, v141
	v_mov_b32_e32 v5, v141
	v_mov_b32_e32 v6, v141
	v_mov_b32_e32 v7, v141
	v_mov_b32_e32 v8, v141
	v_mov_b32_e32 v9, v141
	v_mov_b32_e32 v10, v141
	v_mov_b32_e32 v11, v141
	v_mov_b32_e32 v12, v141
	v_mov_b32_e32 v13, v141
	v_mov_b32_e32 v14, v141
	v_mov_b32_e32 v15, v141

.LBB0_602:
	s_add_u32 s4, s46, 0x80
	s_addc_u32 s5, s47, 0
	s_add_u32 s46, s44, 0x100
	s_addc_u32 s47, s45, 0
	s_mov_b32 s44, 0
	s_add_i32 s76, s44, 2
	s_add_u32 s53, s4, 0x80
	s_addc_u32 s45, s5, 0
	s_add_i32 s54, 0, 0x10000
	s_cmp_eq_u32 s90, s44
	s_cselect_b32 s45, s41, s45
	s_cselect_b32 s44, s40, s53
	v_add_u32_e32 v144, s54, v149
	s_cselect_b32 vcc_hi, s85, s47
	s_cselect_b32 vcc_lo, s84, s46
	s_add_i32 s53, 0, 0x14000
	ds_read_b128 v[140:143], v144
	ds_read_b128 v[152:155], v144 offset:1024
	ds_read_b128 v[156:159], v144 offset:2048
	ds_read_b128 v[166:169], v144 offset:3072
	v_add_u32_e32 v144, s53, v149
	ds_read_b128 v[170:173], v144
	ds_read_b128 v[174:177], v144 offset:1024
	ds_read_b128 v[178:181], v144 offset:2048
	ds_read_b128 v[182:185], v144 offset:3072
	v_lshl_add_u64 v[144:145], s[4:5], 0, v[136:137]
	s_add_i32 m0, s55, 0xc000
	ds_read_b128 v[186:189], v151
	ds_read_b128 v[190:193], v151 offset:1024
	ds_read_b128 v[194:197], v151 offset:2048
	ds_read_b128 v[198:201], v151 offset:3072
	ds_read_b128 v[202:205], v151 offset:4096
	ds_read_b128 v[206:209], v151 offset:5120
	ds_read_b128 v[216:219], v151 offset:6144
	ds_read_b128 v[220:223], v151 offset:7168
	global_load_lds_dwordx4 v[144:145], off
	v_lshl_add_u64 v[144:145], s[4:5], 0, v[138:139]
	s_add_i32 m0, s55, 0xe000
	s_nop 0
	global_load_lds_dwordx4 v[144:145], off
	s_waitcnt vmcnt(8)
	s_waitcnt lgkmcnt(0)
	s_barrier
	s_setprio 1
	s_waitcnt lgkmcnt(0)
	v_mfma_f32_16x16x32_bf16 v[126:129], v[140:143], v[186:189], 0
	v_mfma_f32_16x16x32_bf16 v[118:121], v[156:159], v[186:189], 0
	v_mfma_f32_16x16x32_bf16 v[110:113], v[140:143], v[194:197], 0
	v_mfma_f32_16x16x32_bf16 v[102:105], v[156:159], v[194:197], 0
	v_mfma_f32_16x16x32_bf16 v[94:97], v[140:143], v[202:205], 0
	v_mfma_f32_16x16x32_bf16 v[86:89], v[156:159], v[202:205], 0
	v_mfma_f32_16x16x32_bf16 v[76:79], v[140:143], v[216:219], 0
	v_mfma_f32_16x16x32_bf16 v[68:71], v[156:159], v[216:219], 0
	v_mfma_f32_16x16x32_bf16 v[126:129], v[152:155], v[190:193], v[126:129]
	v_mfma_f32_16x16x32_bf16 v[118:121], v[166:169], v[190:193], v[118:121]
	v_mfma_f32_16x16x32_bf16 v[110:113], v[152:155], v[198:201], v[110:113]
	v_mfma_f32_16x16x32_bf16 v[102:105], v[166:169], v[198:201], v[102:105]
	v_mfma_f32_16x16x32_bf16 v[94:97], v[152:155], v[206:209], v[94:97]
	v_mfma_f32_16x16x32_bf16 v[86:89], v[166:169], v[206:209], v[86:89]
	v_mfma_f32_16x16x32_bf16 v[76:79], v[152:155], v[220:223], v[76:79]
	v_mfma_f32_16x16x32_bf16 v[68:71], v[166:169], v[220:223], v[68:71]
	s_setprio 0
	s_setprio 1
	v_mfma_f32_16x16x32_bf16 v[122:125], v[170:173], v[186:189], 0
	v_mfma_f32_16x16x32_bf16 v[114:117], v[178:181], v[186:189], 0
	v_mfma_f32_16x16x32_bf16 v[106:109], v[170:173], v[194:197], 0
	v_mfma_f32_16x16x32_bf16 v[98:101], v[178:181], v[194:197], 0
	v_mfma_f32_16x16x32_bf16 v[90:93], v[170:173], v[202:205], 0
	v_mfma_f32_16x16x32_bf16 v[82:85], v[178:181], v[202:205], 0
	v_mfma_f32_16x16x32_bf16 v[72:75], v[170:173], v[216:219], 0
	v_mfma_f32_16x16x32_bf16 v[64:67], v[178:181], v[216:219], 0
	v_mfma_f32_16x16x32_bf16 v[122:125], v[174:177], v[190:193], v[122:125]
	v_mfma_f32_16x16x32_bf16 v[114:117], v[182:185], v[190:193], v[114:117]
	v_mfma_f32_16x16x32_bf16 v[106:109], v[174:177], v[198:201], v[106:109]
	v_mfma_f32_16x16x32_bf16 v[98:101], v[182:185], v[198:201], v[98:101]
	v_mfma_f32_16x16x32_bf16 v[90:93], v[174:177], v[206:209], v[90:93]
	v_mfma_f32_16x16x32_bf16 v[82:85], v[182:185], v[206:209], v[82:85]
	v_mfma_f32_16x16x32_bf16 v[72:75], v[174:177], v[220:223], v[72:75]
	v_mfma_f32_16x16x32_bf16 v[64:67], v[182:185], v[220:223], v[64:67]
	s_setprio 0
	s_barrier
	s_add_i32 s54, s54, s49
	v_lshl_add_u64 v[144:145], vcc, 0, v[80:81]
	s_mov_b32 m0, s54
	ds_read_b128 v[186:189], v151 offset:16384
	ds_read_b128 v[190:193], v151 offset:17408
	ds_read_b128 v[194:197], v151 offset:18432
	ds_read_b128 v[198:201], v151 offset:19456
	ds_read_b128 v[202:205], v151 offset:20480
	ds_read_b128 v[206:209], v151 offset:21504
	ds_read_b128 v[216:219], v151 offset:22528
	ds_read_b128 v[220:223], v151 offset:23552
	global_load_lds_dwordx4 v[144:145], off
	s_add_i32 m0, s54, 0x2000
	v_lshl_add_u64 v[160:161], vcc, 0, v[134:135]
	s_add_u32 vcc_lo, vcc_lo, s36
	s_addc_u32 vcc_hi, vcc_hi, 0
	s_add_i32 s53, s53, s49
	global_load_lds_dwordx4 v[160:161], off
	v_lshl_add_u64 v[224:225], vcc, 0, v[80:81]
	s_mov_b32 m0, s53
	v_lshl_add_u64 v[226:227], vcc, 0, v[134:135]
	global_load_lds_dwordx4 v[224:225], off
	s_add_i32 m0, s53, 0x2000
	v_lshl_add_u64 v[228:229], s[44:45], 0, v[130:131]
	global_load_lds_dwordx4 v[226:227], off
	s_mov_b32 m0, s55
	v_lshl_add_u64 v[230:231], s[44:45], 0, v[132:133]
	global_load_lds_dwordx4 v[228:229], off
	s_mov_b32 m0, s74
	s_nop 0
	global_load_lds_dwordx4 v[230:231], off
	s_waitcnt vmcnt(8)
	s_waitcnt lgkmcnt(0)
	s_barrier
	s_setprio 1
	s_waitcnt lgkmcnt(0)
	v_mfma_f32_16x16x32_bf16 v[60:63], v[140:143], v[186:189], 0
	v_mfma_f32_16x16x32_bf16 v[52:55], v[156:159], v[186:189], 0
	v_mfma_f32_16x16x32_bf16 v[44:47], v[140:143], v[194:197], 0
	v_mfma_f32_16x16x32_bf16 v[36:39], v[156:159], v[194:197], 0
	v_mfma_f32_16x16x32_bf16 v[28:31], v[140:143], v[202:205], 0
	v_mfma_f32_16x16x32_bf16 v[20:23], v[156:159], v[202:205], 0
	v_mfma_f32_16x16x32_bf16 v[12:15], v[140:143], v[216:219], 0
	v_mfma_f32_16x16x32_bf16 v[4:7], v[156:159], v[216:219], 0
	v_mfma_f32_16x16x32_bf16 v[60:63], v[152:155], v[190:193], v[60:63]
	v_mfma_f32_16x16x32_bf16 v[52:55], v[166:169], v[190:193], v[52:55]
	v_mfma_f32_16x16x32_bf16 v[44:47], v[152:155], v[198:201], v[44:47]
	v_mfma_f32_16x16x32_bf16 v[36:39], v[166:169], v[198:201], v[36:39]
	v_mfma_f32_16x16x32_bf16 v[28:31], v[152:155], v[206:209], v[28:31]
	v_mfma_f32_16x16x32_bf16 v[20:23], v[166:169], v[206:209], v[20:23]
	v_mfma_f32_16x16x32_bf16 v[12:15], v[152:155], v[220:223], v[12:15]
	v_mfma_f32_16x16x32_bf16 v[4:7], v[166:169], v[220:223], v[4:7]
	s_setprio 0
	s_setprio 1
	v_mfma_f32_16x16x32_bf16 v[56:59], v[170:173], v[186:189], 0
	v_mfma_f32_16x16x32_bf16 v[48:51], v[178:181], v[186:189], 0
	v_mfma_f32_16x16x32_bf16 v[40:43], v[170:173], v[194:197], 0
	v_mfma_f32_16x16x32_bf16 v[32:35], v[178:181], v[194:197], 0
	v_mfma_f32_16x16x32_bf16 v[24:27], v[170:173], v[202:205], 0
	v_mfma_f32_16x16x32_bf16 v[16:19], v[178:181], v[202:205], 0
	v_mfma_f32_16x16x32_bf16 v[8:11], v[170:173], v[216:219], 0
	v_mfma_f32_16x16x32_bf16 v[0:3], v[178:181], v[216:219], 0
	v_mfma_f32_16x16x32_bf16 v[56:59], v[174:177], v[190:193], v[56:59]
	v_mfma_f32_16x16x32_bf16 v[48:51], v[182:185], v[190:193], v[48:51]
	v_mfma_f32_16x16x32_bf16 v[40:43], v[174:177], v[198:201], v[40:43]
	v_mfma_f32_16x16x32_bf16 v[32:35], v[182:185], v[198:201], v[32:35]
	v_mfma_f32_16x16x32_bf16 v[24:27], v[174:177], v[206:209], v[24:27]
	v_mfma_f32_16x16x32_bf16 v[16:19], v[182:185], v[206:209], v[16:19]
	v_mfma_f32_16x16x32_bf16 v[8:11], v[174:177], v[220:223], v[8:11]
	v_mfma_f32_16x16x32_bf16 v[0:3], v[182:185], v[220:223], v[0:3]
	s_setprio 0
	s_barrier
	s_add_i32 s53, 0, 0x18000
	v_add_u32_e32 v146, s53, v149
	s_add_i32 s54, 0, 0x1c000
	ds_read_b128 v[140:143], v146
	ds_read_b128 v[152:155], v146 offset:1024
	ds_read_b128 v[156:159], v146 offset:2048
	ds_read_b128 v[166:169], v146 offset:3072
	v_add_u32_e32 v146, s54, v149
	ds_read_b128 v[170:173], v146
	ds_read_b128 v[174:177], v146 offset:1024
	ds_read_b128 v[178:181], v146 offset:2048
	ds_read_b128 v[182:185], v146 offset:3072
	s_add_u32 s44, s44, s36
	s_addc_u32 s45, s45, 0
	s_mov_b32 m0, s75
	v_lshl_add_u64 v[232:233], s[44:45], 0, v[130:131]
	ds_read_b128 v[186:189], v151 offset:32768
	ds_read_b128 v[190:193], v151 offset:33792
	ds_read_b128 v[194:197], v151 offset:34816
	ds_read_b128 v[198:201], v151 offset:35840
	ds_read_b128 v[202:205], v151 offset:36864
	ds_read_b128 v[206:209], v151 offset:37888
	ds_read_b128 v[216:219], v151 offset:38912
	ds_read_b128 v[220:223], v151 offset:39936
	global_load_lds_dwordx4 v[232:233], off
	v_lshl_add_u64 v[232:233], s[44:45], 0, v[132:133]
	s_mov_b32 m0, s86
	s_nop 0
	global_load_lds_dwordx4 v[232:233], off
	s_waitcnt vmcnt(8)
	s_waitcnt lgkmcnt(0)
	s_barrier
	s_setprio 1
	s_waitcnt lgkmcnt(0)
	v_mfma_f32_16x16x32_bf16 v[126:129], v[140:143], v[186:189], v[126:129]
	v_mfma_f32_16x16x32_bf16 v[118:121], v[156:159], v[186:189], v[118:121]
	v_mfma_f32_16x16x32_bf16 v[110:113], v[140:143], v[194:197], v[110:113]
	v_mfma_f32_16x16x32_bf16 v[102:105], v[156:159], v[194:197], v[102:105]
	v_mfma_f32_16x16x32_bf16 v[94:97], v[140:143], v[202:205], v[94:97]
	v_mfma_f32_16x16x32_bf16 v[86:89], v[156:159], v[202:205], v[86:89]
	v_mfma_f32_16x16x32_bf16 v[76:79], v[140:143], v[216:219], v[76:79]
	v_mfma_f32_16x16x32_bf16 v[68:71], v[156:159], v[216:219], v[68:71]
	v_mfma_f32_16x16x32_bf16 v[126:129], v[152:155], v[190:193], v[126:129]
	v_mfma_f32_16x16x32_bf16 v[118:121], v[166:169], v[190:193], v[118:121]
	v_mfma_f32_16x16x32_bf16 v[110:113], v[152:155], v[198:201], v[110:113]
	v_mfma_f32_16x16x32_bf16 v[102:105], v[166:169], v[198:201], v[102:105]
	v_mfma_f32_16x16x32_bf16 v[94:97], v[152:155], v[206:209], v[94:97]
	v_mfma_f32_16x16x32_bf16 v[86:89], v[166:169], v[206:209], v[86:89]
	v_mfma_f32_16x16x32_bf16 v[76:79], v[152:155], v[220:223], v[76:79]
	v_mfma_f32_16x16x32_bf16 v[68:71], v[166:169], v[220:223], v[68:71]
	s_setprio 0
	s_setprio 1
	v_mfma_f32_16x16x32_bf16 v[122:125], v[170:173], v[186:189], v[122:125]
	v_mfma_f32_16x16x32_bf16 v[114:117], v[178:181], v[186:189], v[114:117]
	v_mfma_f32_16x16x32_bf16 v[106:109], v[170:173], v[194:197], v[106:109]
	v_mfma_f32_16x16x32_bf16 v[98:101], v[178:181], v[194:197], v[98:101]
	v_mfma_f32_16x16x32_bf16 v[90:93], v[170:173], v[202:205], v[90:93]
	v_mfma_f32_16x16x32_bf16 v[82:85], v[178:181], v[202:205], v[82:85]
	v_mfma_f32_16x16x32_bf16 v[72:75], v[170:173], v[216:219], v[72:75]
	v_mfma_f32_16x16x32_bf16 v[64:67], v[178:181], v[216:219], v[64:67]
	v_mfma_f32_16x16x32_bf16 v[122:125], v[174:177], v[190:193], v[122:125]
	v_mfma_f32_16x16x32_bf16 v[114:117], v[182:185], v[190:193], v[114:117]
	v_mfma_f32_16x16x32_bf16 v[106:109], v[174:177], v[198:201], v[106:109]
	v_mfma_f32_16x16x32_bf16 v[98:101], v[182:185], v[198:201], v[98:101]
	v_mfma_f32_16x16x32_bf16 v[90:93], v[174:177], v[206:209], v[90:93]
	v_mfma_f32_16x16x32_bf16 v[82:85], v[182:185], v[206:209], v[82:85]
	v_mfma_f32_16x16x32_bf16 v[72:75], v[174:177], v[220:223], v[72:75]
	v_mfma_f32_16x16x32_bf16 v[64:67], v[182:185], v[220:223], v[64:67]
	s_setprio 0
	s_barrier
	s_add_i32 s44, s53, s49
	v_lshl_add_u64 v[144:145], v[144:145], 0, s[0:1]
	s_mov_b32 m0, s44
	ds_read_b128 v[186:189], v151 offset:49152
	ds_read_b128 v[190:193], v151 offset:50176
	ds_read_b128 v[194:197], v151 offset:51200
	ds_read_b128 v[198:201], v151 offset:52224
	ds_read_b128 v[202:205], v151 offset:53248
	ds_read_b128 v[206:209], v151 offset:54272
	ds_read_b128 v[216:219], v151 offset:55296
	ds_read_b128 v[220:223], v151 offset:56320
	global_load_lds_dwordx4 v[144:145], off
	v_lshl_add_u64 v[144:145], v[160:161], 0, s[0:1]
	s_add_i32 m0, s44, 0x2000
	s_add_i32 s44, s54, s49
	global_load_lds_dwordx4 v[144:145], off
	v_lshl_add_u64 v[144:145], v[224:225], 0, s[0:1]
	s_mov_b32 m0, s44
	s_nop 0
	global_load_lds_dwordx4 v[144:145], off
	v_lshl_add_u64 v[144:145], v[226:227], 0, s[0:1]
	s_add_i32 m0, s44, 0x2000
	s_nop 0
	global_load_lds_dwordx4 v[144:145], off
	v_lshl_add_u64 v[144:145], v[228:229], 0, s[0:1]
	s_mov_b32 m0, s88
	s_nop 0
	global_load_lds_dwordx4 v[144:145], off
	v_lshl_add_u64 v[144:145], v[230:231], 0, s[0:1]
	s_mov_b32 m0, s89
	s_nop 0
	global_load_lds_dwordx4 v[144:145], off
	s_waitcnt vmcnt(8)
	s_waitcnt lgkmcnt(0)
	s_barrier
	s_setprio 1
	s_waitcnt lgkmcnt(0)
	v_mfma_f32_16x16x32_bf16 v[60:63], v[140:143], v[186:189], v[60:63]
	v_mfma_f32_16x16x32_bf16 v[52:55], v[156:159], v[186:189], v[52:55]
	v_mfma_f32_16x16x32_bf16 v[44:47], v[140:143], v[194:197], v[44:47]
	v_mfma_f32_16x16x32_bf16 v[36:39], v[156:159], v[194:197], v[36:39]
	v_mfma_f32_16x16x32_bf16 v[28:31], v[140:143], v[202:205], v[28:31]
	v_mfma_f32_16x16x32_bf16 v[20:23], v[156:159], v[202:205], v[20:23]
	v_mfma_f32_16x16x32_bf16 v[12:15], v[140:143], v[216:219], v[12:15]
	v_mfma_f32_16x16x32_bf16 v[4:7], v[156:159], v[216:219], v[4:7]
	v_mfma_f32_16x16x32_bf16 v[60:63], v[152:155], v[190:193], v[60:63]
	v_mfma_f32_16x16x32_bf16 v[52:55], v[166:169], v[190:193], v[52:55]
	v_mfma_f32_16x16x32_bf16 v[44:47], v[152:155], v[198:201], v[44:47]
	v_mfma_f32_16x16x32_bf16 v[36:39], v[166:169], v[198:201], v[36:39]
	v_mfma_f32_16x16x32_bf16 v[28:31], v[152:155], v[206:209], v[28:31]
	v_mfma_f32_16x16x32_bf16 v[20:23], v[166:169], v[206:209], v[20:23]
	v_mfma_f32_16x16x32_bf16 v[12:15], v[152:155], v[220:223], v[12:15]
	v_mfma_f32_16x16x32_bf16 v[4:7], v[166:169], v[220:223], v[4:7]
	s_setprio 0
	s_setprio 1
	v_mfma_f32_16x16x32_bf16 v[56:59], v[170:173], v[186:189], v[56:59]
	v_mfma_f32_16x16x32_bf16 v[48:51], v[178:181], v[186:189], v[48:51]
	v_mfma_f32_16x16x32_bf16 v[40:43], v[170:173], v[194:197], v[40:43]
	v_mfma_f32_16x16x32_bf16 v[32:35], v[178:181], v[194:197], v[32:35]
	v_mfma_f32_16x16x32_bf16 v[24:27], v[170:173], v[202:205], v[24:27]
	v_mfma_f32_16x16x32_bf16 v[16:19], v[178:181], v[202:205], v[16:19]
	v_mfma_f32_16x16x32_bf16 v[8:11], v[170:173], v[216:219], v[8:11]
	v_mfma_f32_16x16x32_bf16 v[0:3], v[178:181], v[216:219], v[0:3]
	v_mfma_f32_16x16x32_bf16 v[56:59], v[174:177], v[190:193], v[56:59]
	v_mfma_f32_16x16x32_bf16 v[48:51], v[182:185], v[190:193], v[48:51]
	v_mfma_f32_16x16x32_bf16 v[40:43], v[174:177], v[198:201], v[40:43]
	v_mfma_f32_16x16x32_bf16 v[32:35], v[182:185], v[198:201], v[32:35]
	v_mfma_f32_16x16x32_bf16 v[24:27], v[174:177], v[206:209], v[24:27]
	v_mfma_f32_16x16x32_bf16 v[16:19], v[182:185], v[206:209], v[16:19]
	v_mfma_f32_16x16x32_bf16 v[8:11], v[174:177], v[220:223], v[8:11]
	v_mfma_f32_16x16x32_bf16 v[0:3], v[182:185], v[220:223], v[0:3]
	s_setprio 0
	s_barrier
	s_add_u32 s4, s4, 0x100
	s_addc_u32 s5, s5, 0
	s_add_u32 s46, s46, 0x100
	s_addc_u32 s47, s47, 0
	s_cmp_ge_u32 s76, s87
	s_mov_b32 s44, s76
	s_cbranch_scc1 .Lpeel_done_603

.Lpeel_done_603:
	s_and_b64 vcc, exec, s[10:11]
	s_cbranch_vccz .LBB0_606
	s_barrier

.LBB0_650:
	s_add_u32 s4, s46, 0x80
	s_addc_u32 s5, s47, 0
	s_add_u32 s46, s44, 0x100
	s_addc_u32 s47, s45, 0
	s_mov_b32 s44, 0
	s_add_i32 s77, s44, 2
	s_add_u32 vcc_lo, s4, 0x80
	s_addc_u32 s45, s5, 0
	s_add_i32 s53, 0, 0x10000
	s_cmp_eq_u32 s80, s44
	s_cselect_b32 s45, s41, s45
	s_cselect_b32 s44, s40, vcc_lo
	v_add_u32_e32 v144, s53, v149
	s_cselect_b32 vcc_hi, s85, s47
	s_cselect_b32 vcc_lo, s84, s46
	s_add_i32 s54, 0, 0x14000
	ds_read_b128 v[140:143], v144
	ds_read_b128 v[152:155], v144 offset:1024
	ds_read_b128 v[156:159], v144 offset:2048
	ds_read_b128 v[166:169], v144 offset:3072
	v_add_u32_e32 v144, s54, v149
	ds_read_b128 v[170:173], v144
	ds_read_b128 v[174:177], v144 offset:1024
	ds_read_b128 v[178:181], v144 offset:2048
	ds_read_b128 v[182:185], v144 offset:3072
	v_lshl_add_u64 v[144:145], s[4:5], 0, v[136:137]
	s_add_i32 m0, s49, 0xc000
	ds_read_b128 v[186:189], v151
	ds_read_b128 v[190:193], v151 offset:1024
	ds_read_b128 v[194:197], v151 offset:2048
	ds_read_b128 v[198:201], v151 offset:3072
	ds_read_b128 v[202:205], v151 offset:4096
	ds_read_b128 v[206:209], v151 offset:5120
	ds_read_b128 v[216:219], v151 offset:6144
	ds_read_b128 v[220:223], v151 offset:7168
	global_load_lds_dwordx4 v[144:145], off
	v_lshl_add_u64 v[144:145], s[4:5], 0, v[138:139]
	s_add_i32 m0, s49, 0xe000
	s_nop 0
	global_load_lds_dwordx4 v[144:145], off
	s_waitcnt vmcnt(8)
	s_waitcnt lgkmcnt(0)
	s_barrier
	s_setprio 1
	s_waitcnt lgkmcnt(0)
	v_mfma_f32_16x16x32_bf16 v[126:129], v[140:143], v[186:189], 0
	v_mfma_f32_16x16x32_bf16 v[122:125], v[156:159], v[186:189], 0
	v_mfma_f32_16x16x32_bf16 v[110:113], v[140:143], v[194:197], 0
	v_mfma_f32_16x16x32_bf16 v[106:109], v[156:159], v[194:197], 0
	v_mfma_f32_16x16x32_bf16 v[94:97], v[140:143], v[202:205], 0
	v_mfma_f32_16x16x32_bf16 v[90:93], v[156:159], v[202:205], 0
	v_mfma_f32_16x16x32_bf16 v[76:79], v[140:143], v[216:219], 0
	v_mfma_f32_16x16x32_bf16 v[72:75], v[156:159], v[216:219], 0
	v_mfma_f32_16x16x32_bf16 v[126:129], v[152:155], v[190:193], v[126:129]
	v_mfma_f32_16x16x32_bf16 v[122:125], v[166:169], v[190:193], v[122:125]
	v_mfma_f32_16x16x32_bf16 v[110:113], v[152:155], v[198:201], v[110:113]
	v_mfma_f32_16x16x32_bf16 v[106:109], v[166:169], v[198:201], v[106:109]
	v_mfma_f32_16x16x32_bf16 v[94:97], v[152:155], v[206:209], v[94:97]
	v_mfma_f32_16x16x32_bf16 v[90:93], v[166:169], v[206:209], v[90:93]
	v_mfma_f32_16x16x32_bf16 v[76:79], v[152:155], v[220:223], v[76:79]
	v_mfma_f32_16x16x32_bf16 v[72:75], v[166:169], v[220:223], v[72:75]
	s_setprio 0
	s_setprio 1
	v_mfma_f32_16x16x32_bf16 v[118:121], v[170:173], v[186:189], 0
	v_mfma_f32_16x16x32_bf16 v[114:117], v[178:181], v[186:189], 0
	v_mfma_f32_16x16x32_bf16 v[102:105], v[170:173], v[194:197], 0
	v_mfma_f32_16x16x32_bf16 v[98:101], v[178:181], v[194:197], 0
	v_mfma_f32_16x16x32_bf16 v[86:89], v[170:173], v[202:205], 0
	v_mfma_f32_16x16x32_bf16 v[82:85], v[178:181], v[202:205], 0
	v_mfma_f32_16x16x32_bf16 v[68:71], v[170:173], v[216:219], 0
	v_mfma_f32_16x16x32_bf16 v[64:67], v[178:181], v[216:219], 0
	v_mfma_f32_16x16x32_bf16 v[118:121], v[174:177], v[190:193], v[118:121]
	v_mfma_f32_16x16x32_bf16 v[114:117], v[182:185], v[190:193], v[114:117]
	v_mfma_f32_16x16x32_bf16 v[102:105], v[174:177], v[198:201], v[102:105]
	v_mfma_f32_16x16x32_bf16 v[98:101], v[182:185], v[198:201], v[98:101]
	v_mfma_f32_16x16x32_bf16 v[86:89], v[174:177], v[206:209], v[86:89]
	v_mfma_f32_16x16x32_bf16 v[82:85], v[182:185], v[206:209], v[82:85]
	v_mfma_f32_16x16x32_bf16 v[68:71], v[174:177], v[220:223], v[68:71]
	v_mfma_f32_16x16x32_bf16 v[64:67], v[182:185], v[220:223], v[64:67]
	s_setprio 0
	s_barrier
	s_add_i32 s53, s53, s48
	v_lshl_add_u64 v[144:145], vcc, 0, v[80:81]
	s_mov_b32 m0, s53
	ds_read_b128 v[186:189], v151 offset:16384
	ds_read_b128 v[190:193], v151 offset:17408
	ds_read_b128 v[194:197], v151 offset:18432
	ds_read_b128 v[198:201], v151 offset:19456
	ds_read_b128 v[202:205], v151 offset:20480
	ds_read_b128 v[206:209], v151 offset:21504
	ds_read_b128 v[216:219], v151 offset:22528
	ds_read_b128 v[220:223], v151 offset:23552
	global_load_lds_dwordx4 v[144:145], off
	s_add_i32 m0, s53, 0x2000
	v_lshl_add_u64 v[160:161], vcc, 0, v[134:135]
	s_add_u32 vcc_lo, vcc_lo, s36
	s_addc_u32 vcc_hi, vcc_hi, 0
	s_add_i32 s53, s54, s48
	global_load_lds_dwordx4 v[160:161], off
	v_lshl_add_u64 v[224:225], vcc, 0, v[80:81]
	s_mov_b32 m0, s53
	v_lshl_add_u64 v[226:227], vcc, 0, v[134:135]
	global_load_lds_dwordx4 v[224:225], off
	s_add_i32 m0, s53, 0x2000
	v_lshl_add_u64 v[228:229], s[44:45], 0, v[130:131]
	global_load_lds_dwordx4 v[226:227], off
	s_mov_b32 m0, s49
	v_lshl_add_u64 v[230:231], s[44:45], 0, v[132:133]
	global_load_lds_dwordx4 v[228:229], off
	s_mov_b32 m0, s50
	s_nop 0
	global_load_lds_dwordx4 v[230:231], off
	s_waitcnt vmcnt(8)
	s_waitcnt lgkmcnt(0)
	s_barrier
	s_setprio 1
	s_waitcnt lgkmcnt(0)
	v_mfma_f32_16x16x32_bf16 v[60:63], v[140:143], v[186:189], 0
	v_mfma_f32_16x16x32_bf16 v[56:59], v[156:159], v[186:189], 0
	v_mfma_f32_16x16x32_bf16 v[44:47], v[140:143], v[194:197], 0
	v_mfma_f32_16x16x32_bf16 v[40:43], v[156:159], v[194:197], 0
	v_mfma_f32_16x16x32_bf16 v[28:31], v[140:143], v[202:205], 0
	v_mfma_f32_16x16x32_bf16 v[24:27], v[156:159], v[202:205], 0
	v_mfma_f32_16x16x32_bf16 v[12:15], v[140:143], v[216:219], 0
	v_mfma_f32_16x16x32_bf16 v[8:11], v[156:159], v[216:219], 0
	v_mfma_f32_16x16x32_bf16 v[60:63], v[152:155], v[190:193], v[60:63]
	v_mfma_f32_16x16x32_bf16 v[56:59], v[166:169], v[190:193], v[56:59]
	v_mfma_f32_16x16x32_bf16 v[44:47], v[152:155], v[198:201], v[44:47]
	v_mfma_f32_16x16x32_bf16 v[40:43], v[166:169], v[198:201], v[40:43]
	v_mfma_f32_16x16x32_bf16 v[28:31], v[152:155], v[206:209], v[28:31]
	v_mfma_f32_16x16x32_bf16 v[24:27], v[166:169], v[206:209], v[24:27]
	v_mfma_f32_16x16x32_bf16 v[12:15], v[152:155], v[220:223], v[12:15]
	v_mfma_f32_16x16x32_bf16 v[8:11], v[166:169], v[220:223], v[8:11]
	s_setprio 0
	s_setprio 1
	v_mfma_f32_16x16x32_bf16 v[52:55], v[170:173], v[186:189], 0
	v_mfma_f32_16x16x32_bf16 v[48:51], v[178:181], v[186:189], 0
	v_mfma_f32_16x16x32_bf16 v[36:39], v[170:173], v[194:197], 0
	v_mfma_f32_16x16x32_bf16 v[32:35], v[178:181], v[194:197], 0
	v_mfma_f32_16x16x32_bf16 v[20:23], v[170:173], v[202:205], 0
	v_mfma_f32_16x16x32_bf16 v[16:19], v[178:181], v[202:205], 0
	v_mfma_f32_16x16x32_bf16 v[4:7], v[170:173], v[216:219], 0
	v_mfma_f32_16x16x32_bf16 v[0:3], v[178:181], v[216:219], 0
	v_mfma_f32_16x16x32_bf16 v[52:55], v[174:177], v[190:193], v[52:55]
	v_mfma_f32_16x16x32_bf16 v[48:51], v[182:185], v[190:193], v[48:51]
	v_mfma_f32_16x16x32_bf16 v[36:39], v[174:177], v[198:201], v[36:39]
	v_mfma_f32_16x16x32_bf16 v[32:35], v[182:185], v[198:201], v[32:35]
	v_mfma_f32_16x16x32_bf16 v[20:23], v[174:177], v[206:209], v[20:23]
	v_mfma_f32_16x16x32_bf16 v[16:19], v[182:185], v[206:209], v[16:19]
	v_mfma_f32_16x16x32_bf16 v[4:7], v[174:177], v[220:223], v[4:7]
	v_mfma_f32_16x16x32_bf16 v[0:3], v[182:185], v[220:223], v[0:3]
	s_setprio 0
	s_barrier
	s_add_i32 s53, 0, 0x18000
	v_add_u32_e32 v146, s53, v149
	s_add_i32 s54, 0, 0x1c000
	ds_read_b128 v[140:143], v146
	ds_read_b128 v[152:155], v146 offset:1024
	ds_read_b128 v[156:159], v146 offset:2048
	ds_read_b128 v[166:169], v146 offset:3072
	v_add_u32_e32 v146, s54, v149
	ds_read_b128 v[170:173], v146
	ds_read_b128 v[174:177], v146 offset:1024
	ds_read_b128 v[178:181], v146 offset:2048
	ds_read_b128 v[182:185], v146 offset:3072
	s_add_u32 s44, s44, s36
	s_addc_u32 s45, s45, 0
	s_mov_b32 m0, s55
	v_lshl_add_u64 v[232:233], s[44:45], 0, v[130:131]
	ds_read_b128 v[186:189], v151 offset:32768
	ds_read_b128 v[190:193], v151 offset:33792
	ds_read_b128 v[194:197], v151 offset:34816
	ds_read_b128 v[198:201], v151 offset:35840
	ds_read_b128 v[202:205], v151 offset:36864
	ds_read_b128 v[206:209], v151 offset:37888
	ds_read_b128 v[216:219], v151 offset:38912
	ds_read_b128 v[220:223], v151 offset:39936
	global_load_lds_dwordx4 v[232:233], off
	v_lshl_add_u64 v[232:233], s[44:45], 0, v[132:133]
	s_mov_b32 m0, s56
	s_nop 0
	global_load_lds_dwordx4 v[232:233], off
	s_waitcnt vmcnt(8)
	s_waitcnt lgkmcnt(0)
	s_barrier
	s_setprio 1
	s_waitcnt lgkmcnt(0)
	v_mfma_f32_16x16x32_bf16 v[126:129], v[140:143], v[186:189], v[126:129]
	v_mfma_f32_16x16x32_bf16 v[122:125], v[156:159], v[186:189], v[122:125]
	v_mfma_f32_16x16x32_bf16 v[110:113], v[140:143], v[194:197], v[110:113]
	v_mfma_f32_16x16x32_bf16 v[106:109], v[156:159], v[194:197], v[106:109]
	v_mfma_f32_16x16x32_bf16 v[94:97], v[140:143], v[202:205], v[94:97]
	v_mfma_f32_16x16x32_bf16 v[90:93], v[156:159], v[202:205], v[90:93]
	v_mfma_f32_16x16x32_bf16 v[76:79], v[140:143], v[216:219], v[76:79]
	v_mfma_f32_16x16x32_bf16 v[72:75], v[156:159], v[216:219], v[72:75]
	v_mfma_f32_16x16x32_bf16 v[126:129], v[152:155], v[190:193], v[126:129]
	v_mfma_f32_16x16x32_bf16 v[122:125], v[166:169], v[190:193], v[122:125]
	v_mfma_f32_16x16x32_bf16 v[110:113], v[152:155], v[198:201], v[110:113]
	v_mfma_f32_16x16x32_bf16 v[106:109], v[166:169], v[198:201], v[106:109]
	v_mfma_f32_16x16x32_bf16 v[94:97], v[152:155], v[206:209], v[94:97]
	v_mfma_f32_16x16x32_bf16 v[90:93], v[166:169], v[206:209], v[90:93]
	v_mfma_f32_16x16x32_bf16 v[76:79], v[152:155], v[220:223], v[76:79]
	v_mfma_f32_16x16x32_bf16 v[72:75], v[166:169], v[220:223], v[72:75]
	s_setprio 0
	s_setprio 1
	v_mfma_f32_16x16x32_bf16 v[118:121], v[170:173], v[186:189], v[118:121]
	v_mfma_f32_16x16x32_bf16 v[114:117], v[178:181], v[186:189], v[114:117]
	v_mfma_f32_16x16x32_bf16 v[102:105], v[170:173], v[194:197], v[102:105]
	v_mfma_f32_16x16x32_bf16 v[98:101], v[178:181], v[194:197], v[98:101]
	v_mfma_f32_16x16x32_bf16 v[86:89], v[170:173], v[202:205], v[86:89]
	v_mfma_f32_16x16x32_bf16 v[82:85], v[178:181], v[202:205], v[82:85]
	v_mfma_f32_16x16x32_bf16 v[68:71], v[170:173], v[216:219], v[68:71]
	v_mfma_f32_16x16x32_bf16 v[64:67], v[178:181], v[216:219], v[64:67]
	v_mfma_f32_16x16x32_bf16 v[118:121], v[174:177], v[190:193], v[118:121]
	v_mfma_f32_16x16x32_bf16 v[114:117], v[182:185], v[190:193], v[114:117]
	v_mfma_f32_16x16x32_bf16 v[102:105], v[174:177], v[198:201], v[102:105]
	v_mfma_f32_16x16x32_bf16 v[98:101], v[182:185], v[198:201], v[98:101]
	v_mfma_f32_16x16x32_bf16 v[86:89], v[174:177], v[206:209], v[86:89]
	v_mfma_f32_16x16x32_bf16 v[82:85], v[182:185], v[206:209], v[82:85]
	v_mfma_f32_16x16x32_bf16 v[68:71], v[174:177], v[220:223], v[68:71]
	v_mfma_f32_16x16x32_bf16 v[64:67], v[182:185], v[220:223], v[64:67]
	s_setprio 0
	s_barrier
	s_add_i32 s44, s53, s48
	v_lshl_add_u64 v[144:145], v[144:145], 0, s[0:1]
	s_mov_b32 m0, s44
	ds_read_b128 v[186:189], v151 offset:49152
	ds_read_b128 v[190:193], v151 offset:50176
	ds_read_b128 v[194:197], v151 offset:51200
	ds_read_b128 v[198:201], v151 offset:52224
	ds_read_b128 v[202:205], v151 offset:53248
	ds_read_b128 v[206:209], v151 offset:54272
	ds_read_b128 v[216:219], v151 offset:55296
	ds_read_b128 v[220:223], v151 offset:56320
	global_load_lds_dwordx4 v[144:145], off
	v_lshl_add_u64 v[144:145], v[160:161], 0, s[0:1]
	s_add_i32 m0, s44, 0x2000
	s_add_i32 s44, s54, s48
	global_load_lds_dwordx4 v[144:145], off
	v_lshl_add_u64 v[144:145], v[224:225], 0, s[0:1]
	s_mov_b32 m0, s44
	s_nop 0
	global_load_lds_dwordx4 v[144:145], off
	v_lshl_add_u64 v[144:145], v[226:227], 0, s[0:1]
	s_add_i32 m0, s44, 0x2000
	s_nop 0
	global_load_lds_dwordx4 v[144:145], off
	v_lshl_add_u64 v[144:145], v[228:229], 0, s[0:1]
	s_mov_b32 m0, s74
	s_nop 0
	global_load_lds_dwordx4 v[144:145], off
	v_lshl_add_u64 v[144:145], v[230:231], 0, s[0:1]
	s_mov_b32 m0, s75
	s_nop 0
	global_load_lds_dwordx4 v[144:145], off
	s_waitcnt vmcnt(8)
	s_waitcnt lgkmcnt(0)
	s_barrier
	s_setprio 1
	s_waitcnt lgkmcnt(0)
	v_mfma_f32_16x16x32_bf16 v[60:63], v[140:143], v[186:189], v[60:63]
	v_mfma_f32_16x16x32_bf16 v[56:59], v[156:159], v[186:189], v[56:59]
	v_mfma_f32_16x16x32_bf16 v[44:47], v[140:143], v[194:197], v[44:47]
	v_mfma_f32_16x16x32_bf16 v[40:43], v[156:159], v[194:197], v[40:43]
	v_mfma_f32_16x16x32_bf16 v[28:31], v[140:143], v[202:205], v[28:31]
	v_mfma_f32_16x16x32_bf16 v[24:27], v[156:159], v[202:205], v[24:27]
	v_mfma_f32_16x16x32_bf16 v[12:15], v[140:143], v[216:219], v[12:15]
	v_mfma_f32_16x16x32_bf16 v[8:11], v[156:159], v[216:219], v[8:11]
	v_mfma_f32_16x16x32_bf16 v[60:63], v[152:155], v[190:193], v[60:63]
	v_mfma_f32_16x16x32_bf16 v[56:59], v[166:169], v[190:193], v[56:59]
	v_mfma_f32_16x16x32_bf16 v[44:47], v[152:155], v[198:201], v[44:47]
	v_mfma_f32_16x16x32_bf16 v[40:43], v[166:169], v[198:201], v[40:43]
	v_mfma_f32_16x16x32_bf16 v[28:31], v[152:155], v[206:209], v[28:31]
	v_mfma_f32_16x16x32_bf16 v[24:27], v[166:169], v[206:209], v[24:27]
	v_mfma_f32_16x16x32_bf16 v[12:15], v[152:155], v[220:223], v[12:15]
	v_mfma_f32_16x16x32_bf16 v[8:11], v[166:169], v[220:223], v[8:11]
	s_setprio 0
	s_setprio 1
	v_mfma_f32_16x16x32_bf16 v[52:55], v[170:173], v[186:189], v[52:55]
	v_mfma_f32_16x16x32_bf16 v[48:51], v[178:181], v[186:189], v[48:51]
	v_mfma_f32_16x16x32_bf16 v[36:39], v[170:173], v[194:197], v[36:39]
	v_mfma_f32_16x16x32_bf16 v[32:35], v[178:181], v[194:197], v[32:35]
	v_mfma_f32_16x16x32_bf16 v[20:23], v[170:173], v[202:205], v[20:23]
	v_mfma_f32_16x16x32_bf16 v[16:19], v[178:181], v[202:205], v[16:19]
	v_mfma_f32_16x16x32_bf16 v[4:7], v[170:173], v[216:219], v[4:7]
	v_mfma_f32_16x16x32_bf16 v[0:3], v[178:181], v[216:219], v[0:3]
	v_mfma_f32_16x16x32_bf16 v[52:55], v[174:177], v[190:193], v[52:55]
	v_mfma_f32_16x16x32_bf16 v[48:51], v[182:185], v[190:193], v[48:51]
	v_mfma_f32_16x16x32_bf16 v[36:39], v[174:177], v[198:201], v[36:39]
	v_mfma_f32_16x16x32_bf16 v[32:35], v[182:185], v[198:201], v[32:35]
	v_mfma_f32_16x16x32_bf16 v[20:23], v[174:177], v[206:209], v[20:23]
	v_mfma_f32_16x16x32_bf16 v[16:19], v[182:185], v[206:209], v[16:19]
	v_mfma_f32_16x16x32_bf16 v[4:7], v[174:177], v[220:223], v[4:7]
	v_mfma_f32_16x16x32_bf16 v[0:3], v[182:185], v[220:223], v[0:3]
	s_setprio 0
	s_barrier
	s_add_u32 s4, s4, 0x100
	s_addc_u32 s5, s5, 0
	s_add_u32 s46, s46, 0x100
	s_addc_u32 s47, s47, 0
	s_cmp_ge_u32 s77, s83
	s_mov_b32 s44, s77
	s_cbranch_scc1 .Lpeel_done_651
